# v18 + in-XCD stagger of G2/G4 (blocks >=128 start 3x s_sleep127 late) for layers 0-2 only (StaticOrder path)
# baseline (speedup 1.0000x reference)
;     __device__ void init(int N, int G, int c) { S.init(NBATCH * SEQ, N, G, c); }
; template <class Epi, class Sched, bool ALIGN_EPI = false, bool SP2 = false>
; __device__ __forceinline__ void gemm_phase(PG8_LAS unsigned char* lds, const Gemm g, const Sched& S, const Epi& E) {
;     int tid_o = threadIdx.x; asm volatile("" : "+v"(tid_o));
;     const int tid = tid_o, wid = __builtin_amdgcn_readfirstlane(tid >> 6), lane = tid & 63, wr = wid >> 2, wc = wid & 3, fr = lane & 15, fq = lane >> 4;
; __global__ void __launch_bounds__(512, 2) hybrid_fwd(Params Parg) {
;     ...
;         { const Params P = fresh_params(); const int G = gridDim.x, blk = blockIdx.x;
;           const float* modl = (const float*)(P.ws + WS_MOD) + (size_t)l * 17 * MODW;
;           pg8::Gemm g{(const pg8::bf16_t*)(P.ws + WS_H), (const pg8::bf16_t*)(P.ws + (size_t)(l & 1) * WS_WBUF + WS_W_OUT), ROWS, DM, DM};
;           EpiResid E{P.out, (float*)(P.ws + WS_XC), modl + 2 * DM};
;           if (lat_only) { LatOrder S; S.init(DM, G, blk); pg8::gemm_phase<EpiResid, LatOrder, RES_ALIGN, true>(ldsl, g, S, E); }
;           else { pg8::StaticOrder S; S.init(ROWS, DM, G, blk); pg8::gemm_phase<EpiResid, pg8::StaticOrder, RES_ALIGN, true>(ldsl, g, S, E); } }
.LBB0_838:
	s_or_b64 exec, exec, s[0:1]
	s_mov_b64 s[0:1], s[28:29]
	s_waitcnt lgkmcnt(0)
	s_barrier
	s_load_dwordx4 s[44:47], s[0:1], 0x98
	s_mul_i32 s64, s6, 0x19800
	s_lshl_b64 s[6:7], s[64:65], 2
	v_readlane_b32 s12, v253, 52
	v_readlane_b32 s13, v253, 53
	s_waitcnt lgkmcnt(0)
	s_add_u32 s0, s46, s6
	v_writelane_b32 v255, s6, 30
	s_addc_u32 s1, s47, s7
	s_add_u32 s8, s46, 0x5500000
	s_addc_u32 s9, s47, 0
	s_add_u32 s10, s46, s70
	s_addc_u32 s11, s47, 0
	s_add_u32 s28, s10, 0x980000
	s_addc_u32 s29, s11, 0
	v_writelane_b32 v255, s7, 31
	s_add_u32 s64, s46, 0x4500000
	s_addc_u32 s40, s47, 0
	v_readlane_b32 s6, v255, 3
	s_add_u32 s41, s0, 0x102000
	v_readlane_b32 s7, v255, 4
	v_cndmask_b32_e64 v0, 0, 1, s[12:13]
	s_addc_u32 s0, s1, 0
	s_and_b64 vcc, exec, s[6:7]
	v_cmp_ne_u32_e64 s[6:7], 1, v0
	s_mov_b64 s[10:11], -1
	s_nop 0
	v_writelane_b32 v255, s6, 32
	s_nop 1
	v_writelane_b32 v255, s7, 33
	s_cbranch_vccz .LBB0_860
	v_readlane_b32 s6, v255, 32
	v_mov_b32_e32 v12, v200
	v_readlane_b32 s7, v255, 33
	s_and_b64 vcc, exec, s[6:7]
	v_readfirstlane_b32 s12, v12
	s_cbranch_vccnz .LBB0_859
	s_cmp_lt_u32 s2, 128
	s_cbranch_scc1 .Lg2gs_go
	s_mov_b32 s100, 3

; #define PG8_STAGE(bufoff, gbase, voff) do { _Pragma("unroll") for (int _i = 0; _i < 2; ++_i) \
;         __builtin_amdgcn_global_load_lds((const unsigned*)((const char*)(gbase) + (voff)[_i]), (PG8_LAS unsigned*)(lds + (bufoff) + ldsw + _i * 8192), 16, 0, 0); } while (0)
; #define PG8_WAIT_V(n) asm volatile("s_waitcnt vmcnt(" #n ")" ::: "memory")
; #define PG8_BAR __builtin_amdgcn_s_barrier()
;     __device__ bool next(int i, pg8::Unit& u) const { if (i != 0) return false; u.pm = pm; u.pn = pn; return true; }
; template <class Epi, class Sched, bool ALIGN_EPI = false, bool SP2 = false>
; __device__ __forceinline__ void gemm_phase(PG8_LAS unsigned char* lds, const Gemm g, const Sched& S, const Epi& E) {
;     int tid_o = threadIdx.x; asm volatile("" : "+v"(tid_o));
;     const int tid = tid_o, wid = __builtin_amdgcn_readfirstlane(tid >> 6), lane = tid & 63, wr = wid >> 2, wc = wid & 3, fr = lane & 15, fq = lane >> 4;
;     const int K = g.K, nt = K / BK;
;     unsigned voffA[2], voffB[2];
; #pragma unroll
;     for (int i = 0; i < 2; ++i) { int R, C; stage_rc(tid * 16 + i * 8192, R, C); const int Rb = Epi::PERM ? ((R & ~31) + perm32(R & 31)) : R;
;         voffA[i] = (unsigned)(R * K + C) * 2u; voffB[i] = (unsigned)(Rb * K + C) * 2u; }
;     const size_t kstep = (size_t)(BK * 2);
;     const size_t hstep = (size_t)HALF * K * 2;
;     const size_t tstep = 2 * hstep;
;     const unsigned ldsw = (unsigned)wid * 1024u;
;     const int aoff = lds_byte(wr * 64 + fr, fq * 8), boff = lds_byte(wc * 32 + fr, fq * 8);
;     ...
;     Unit cur, nxt; int ui = 0;
;     if (!S.next(0, cur)) return;
;     f32x4 acc[2][2][4][2];
; #pragma unroll
;     for (int a = 0; a < 2; ++a)
; #pragma unroll
;         for (int b = 0; b < 2; ++b)
; #pragma unroll
;             for (int m = 0; m < 4; ++m)
; #pragma unroll
;                 for (int n = 0; n < 2; ++n) acc[a][b][m][n] = (f32x4){0.f, 0.f, 0.f, 0.f};
;     bf16x8 At[4][2], B0[2][2], B1[2][2];
;     const char* cA = (const char*)g.A + (size_t)cur.pm * tstep; const char* cB = (const char*)g.Bt + (size_t)cur.pn * tstep;
;     S.a_ready(cur);
;     if constexpr (SP2) {
;         PG8_STAGE(PG8_SB(0, 0), cB, voffB); PG8_STAGE(PG8_SB(0, 1), cB + hstep, voffB); PG8_STAGE(PG8_SA(0, 0), cA, voffA); PG8_STAGE(PG8_SA(0, 1), cA + hstep, voffA);
;         if (wr == 1) PG8_BAR;
;         PG8_WAIT_V(2); PG8_BAR;
.Lg2gs_go:
	v_lshlrev_b32_e32 v0, 4, v12
	v_add_u32_e32 v1, 0x2000, v0
	v_ashrrev_i32_e32 v2, 31, v1
	v_lshrrev_b32_e32 v2, 22, v2
	v_add_u32_e32 v2, v1, v2
	s_waitcnt vmcnt(2)
	v_ashrrev_i32_e32 v8, 10, v2
	v_mul_i32_i24_e32 v2, 0x400, v8
	v_sub_u32_e32 v1, v1, v2
	v_lshrrev_b32_e32 v2, 4, v1
	v_bitop3_b32 v1, v2, v1, 32 bitop3:0x6c
	v_ashrrev_i32_e32 v2, 31, v1
	v_lshrrev_b32_e32 v2, 26, v2
	v_add_u32_e32 v2, v1, v2
	v_ashrrev_i32_e32 v9, 6, v2
	v_and_b32_e32 v2, 0xc0, v2
	v_sub_u32_e32 v1, v1, v2
	v_ashrrev_i16_sdwa v1, v203, sext(v1) dst_sel:DWORD dst_unused:UNUSED_PAD src0_sel:DWORD src1_sel:BYTE_0
	v_bfe_i32 v11, v1, 0, 16
	v_bfe_i32 v1, v12, 27, 1
	v_lshrrev_b32_e32 v1, 22, v1
	v_add_u32_e32 v1, v0, v1
	v_and_b32_e32 v1, 0xfffffc00, v1
	v_sub_u32_e32 v0, v0, v1
	v_lshrrev_b32_e32 v1, 4, v0
	v_bitop3_b32 v0, v1, v0, 32 bitop3:0x6c
	v_ashrrev_i32_e32 v2, 31, v12
	v_lshlrev_b32_e32 v3, 3, v8
	v_ashrrev_i32_e32 v1, 31, v0
	v_lshrrev_b32_e32 v2, 26, v2
	v_and_b32_e32 v3, 0x1ffff0, v3
	v_lshlrev_b32_e32 v4, 5, v8
	v_lshrrev_b32_e32 v1, 26, v1
	v_add_u32_e32 v2, v12, v2
	v_add_u32_e32 v3, v9, v3
	v_and_b32_e32 v10, 32, v4
	v_add_u32_e32 v1, v0, v1
	v_ashrrev_i32_e32 v14, 6, v2
	s_ashr_i32 s15, s12, 6
	v_lshl_or_b32 v3, v3, 10, v10
	v_ashrrev_i32_e32 v13, 6, v1
	v_lshlrev_b32_e32 v2, 3, v14
	v_and_b32_e32 v1, 0xc0, v1
	s_ashr_i32 s13, s12, 8
	s_lshl_b32 s1, s15, 10
	v_add_lshl_u32 v146, v3, v11, 1
	v_and_b32_e32 v2, 0x1ffff0, v2
	v_lshlrev_b32_e32 v3, 5, v14
	v_sub_u32_e32 v0, v0, v1
	v_readlane_b32 s10, v254, 5
	v_add_u32_e32 v2, v13, v2
	v_and_b32_e32 v15, 32, v3
	v_ashrrev_i16_sdwa v0, v203, sext(v0) dst_sel:DWORD dst_unused:UNUSED_PAD src0_sel:DWORD src1_sel:BYTE_0
	v_readlane_b32 s11, v254, 6
	s_add_u32 s52, s28, s10
	v_lshl_or_b32 v2, v2, 10, v15
	v_bfe_i32 v16, v0, 0, 16
	s_addc_u32 s53, s29, s11
	s_add_i32 s58, s1, 0
	v_add_lshl_u32 v128, v2, v16, 1
	s_add_i32 m0, s58, 0x10000
	v_readlane_b32 s6, v254, 33
	global_load_lds_dwordx4 v128, s[52:53]
	s_add_i32 m0, s58, 0x12000
	s_add_u32 s10, s52, 0x40000
	global_load_lds_dwordx4 v146, s[52:53]
	s_addc_u32 s11, s53, 0
	s_add_i32 m0, s58, 0x14000
	v_readlane_b32 s7, v254, 34
	global_load_lds_dwordx4 v128, s[10:11]
	s_add_i32 m0, s58, 0x16000
	s_add_u32 s50, s8, s6
	s_addc_u32 s51, s9, s7
	s_add_i32 s18, s58, 0x2000
	global_load_lds_dwordx4 v146, s[10:11]
	s_mov_b32 m0, s58
	s_add_u32 s10, s50, 0x40000
	global_load_lds_dwordx4 v128, s[50:51]
	s_mov_b32 m0, s18
	s_addc_u32 s11, s51, 0
	s_add_i32 s19, s58, 0x4000
	global_load_lds_dwordx4 v146, s[50:51]
	s_mov_b32 m0, s19
	s_add_i32 s59, s58, 0x6000
	global_load_lds_dwordx4 v128, s[10:11]
	s_mov_b32 m0, s59
	v_mov_b32_e32 v147, v129
	global_load_lds_dwordx4 v146, s[10:11]
	s_cmp_eq_u32 s13, 1
	v_lshl_add_u64 v[6:7], s[52:53], 0, v[128:129]
	v_lshl_add_u64 v[4:5], s[52:53], 0, v[146:147]
	v_lshl_add_u64 v[0:1], s[50:51], 0, v[128:129]
	s_cselect_b64 s[10:11], -1, 0
	s_cmp_lg_u32 s13, 1
	v_lshl_add_u64 v[2:3], s[50:51], 0, v[146:147]
	s_cbranch_scc1 .LBB0_842
	s_barrier

; #define PG8_LAS __attribute__((address_space(3)))
;     __device__ void init(int N, int G, int c) { S.init(NBATCH * SEQ, N, G, c); }
; template <class Epi, class Sched, bool ALIGN_EPI = false, bool SP2 = false>
; __device__ __forceinline__ void gemm_phase(PG8_LAS unsigned char* lds, const Gemm g, const Sched& S, const Epi& E) {
;     int tid_o = threadIdx.x; asm volatile("" : "+v"(tid_o));
;     const int tid = tid_o, wid = __builtin_amdgcn_readfirstlane(tid >> 6), lane = tid & 63, wr = wid >> 2, wc = wid & 3, fr = lane & 15, fq = lane >> 4;
;     const int K = g.K, nt = K / BK;
;     unsigned voffA[2], voffB[2];
; #pragma unroll
;     for (int i = 0; i < 2; ++i) { int R, C; stage_rc(tid * 16 + i * 8192, R, C); const int Rb = Epi::PERM ? ((R & ~31) + perm32(R & 31)) : R;
;         voffA[i] = (unsigned)(R * K + C) * 2u; voffB[i] = (unsigned)(Rb * K + C) * 2u; }
;     const size_t kstep = (size_t)(BK * 2);
;     const size_t hstep = (size_t)HALF * K * 2;
;     const size_t tstep = 2 * hstep;
;     const unsigned ldsw = (unsigned)wid * 1024u;
;     const int aoff = lds_byte(wr * 64 + fr, fq * 8), boff = lds_byte(wc * 32 + fr, fq * 8);
; __global__ void __launch_bounds__(512, 2) hybrid_fwd(Params Parg) {
;     ...
;         { const Params P = fresh_params(); const int G = gridDim.x, blk = blockIdx.x;
;           const float* modl = (const float*)(P.ws + WS_MOD) + (size_t)l * 17 * MODW;
;           pg8::Gemm g{(const pg8::bf16_t*)(P.ws + WS_PROJ), (const pg8::bf16_t*)(P.ws + (size_t)(l & 1) * WS_WBUF + WS_W_FO), ROWS, DM, FFH};
;           EpiResid E{P.out, (float*)(P.ws + WS_XC), modl + 5 * DM};
;           if (lat_only) { LatOrder S; S.init(DM, G, blk); pg8::gemm_phase<EpiResid, LatOrder, RES_ALIGN, true>(ldsl, g, S, E); }
;           else { pg8::StaticOrder S; S.init(ROWS, DM, G, blk); pg8::gemm_phase<EpiResid, pg8::StaticOrder, RES_ALIGN, true>(ldsl, g, S, E); }
;           if (l + 1 < DEPTH) { __syncthreads(); convert_weights(P, l + 1, lds, lat_only ? 0 : 64); } }
.LBB0_1079:
	s_mov_b32 s12, s70
	s_movk_i32 s70, 0xf700
	s_mov_b32 s6, 0x38e38e39
	s_or_b64 exec, exec, s[10:11]
	s_mov_b64 s[0:1], s[18:19]
	s_waitcnt lgkmcnt(0)
	s_barrier
	s_load_dwordx4 s[52:55], s[0:1], 0x98
	s_load_dwordx4 s[40:43], s[0:1], 0x80
	s_load_dwordx2 s[34:35], s[0:1], 0x38
	s_load_dwordx2 s[36:37], s[0:1], 0x70
	v_readlane_b32 s0, v255, 30
	v_readlane_b32 s1, v255, 31
	s_waitcnt lgkmcnt(0)
	s_add_u32 s0, s54, s0
	s_addc_u32 s1, s55, s1
	s_add_u32 s8, s54, 0x9d00000
	s_addc_u32 s9, s55, 0
	s_add_u32 s10, s54, s12
	s_addc_u32 s11, s55, 0
	s_add_u32 s28, s10, 0x1680000
	s_addc_u32 s29, s11, 0
	s_add_u32 s64, s54, 0x4500000
	s_addc_u32 s10, s55, 0
	v_readlane_b32 s12, v255, 3
	s_add_u32 s11, s0, 0x105000
	v_readlane_b32 s13, v255, 4
	s_addc_u32 s24, s1, 0
	s_mov_b64 s[0:1], -1
	s_and_b64 vcc, exec, s[12:13]
	s_cbranch_vccz .LBB0_1105
	v_readlane_b32 s0, v255, 32
	v_mov_b32_e32 v12, v200
	v_readlane_b32 s1, v255, 33
	s_and_b64 vcc, exec, s[0:1]
	v_readfirstlane_b32 s12, v12
	s_cbranch_vccnz .LBB0_1104
	s_cmp_lt_u32 s2, 128
	s_cbranch_scc1 .Lg4gs_go
	s_mov_b32 s100, 3

; #define PG8_LAS __attribute__((address_space(3)))
; #define PG8_BAR __builtin_amdgcn_s_barrier()
; template <class Epi, class Sched, bool ALIGN_EPI = false, bool SP2 = false>
; __device__ __forceinline__ void gemm_phase(PG8_LAS unsigned char* lds, const Gemm g, const Sched& S, const Epi& E) {
;     int tid_o = threadIdx.x; asm volatile("" : "+v"(tid_o));
;     const int tid = tid_o, wid = __builtin_amdgcn_readfirstlane(tid >> 6), lane = tid & 63, wr = wid >> 2, wc = wid & 3, fr = lane & 15, fq = lane >> 4;
;     const int K = g.K, nt = K / BK;
;     unsigned voffA[2], voffB[2];
; #pragma unroll
;     for (int i = 0; i < 2; ++i) { int R, C; stage_rc(tid * 16 + i * 8192, R, C); const int Rb = Epi::PERM ? ((R & ~31) + perm32(R & 31)) : R;
;         voffA[i] = (unsigned)(R * K + C) * 2u; voffB[i] = (unsigned)(Rb * K + C) * 2u; }
;     const size_t kstep = (size_t)(BK * 2);
;     const size_t hstep = (size_t)HALF * K * 2;
;     const size_t tstep = 2 * hstep;
;     const unsigned ldsw = (unsigned)wid * 1024u;
;     const int aoff = lds_byte(wr * 64 + fr, fq * 8), boff = lds_byte(wc * 32 + fr, fq * 8);
;     ...
;     Unit cur, nxt; int ui = 0;
;     if (!S.next(0, cur)) return;
;     f32x4 acc[2][2][4][2];
; #pragma unroll
;     for (int a = 0; a < 2; ++a)
; #pragma unroll
;         for (int b = 0; b < 2; ++b)
; #pragma unroll
;             for (int m = 0; m < 4; ++m)
; #pragma unroll
;                 for (int n = 0; n < 2; ++n) acc[a][b][m][n] = (f32x4){0.f, 0.f, 0.f, 0.f};
;     bf16x8 At[4][2], B0[2][2], B1[2][2];
;     const char* cA = (const char*)g.A + (size_t)cur.pm * tstep; const char* cB = (const char*)g.Bt + (size_t)cur.pn * tstep;
;     S.a_ready(cur);
;     if constexpr (SP2) {
;         PG8_STAGE(PG8_SB(0, 0), cB, voffB); PG8_STAGE(PG8_SB(0, 1), cB + hstep, voffB); PG8_STAGE(PG8_SA(0, 0), cA, voffA); PG8_STAGE(PG8_SA(0, 1), cA + hstep, voffA);
;         if (wr == 1) PG8_BAR;
;         PG8_WAIT_V(2); PG8_BAR;
;         PG8_STAGE(PG8_SB(1, 0), cB + kstep, voffB); PG8_STAGE(PG8_SA(1, 0), cA + kstep, voffA); PG8_STAGE(PG8_SB(1, 1), cB + hstep + kstep, voffB);
;         PG8_WAIT_V(6); PG8_BAR;
;     } else {
;         PG8_STAGE(PG8_SB(0, 0), cB, voffB); PG8_STAGE(PG8_SA(0, 0), cA, voffA); PG8_STAGE(PG8_SB(0, 1), cB + hstep, voffB); PG8_STAGE(PG8_SA(0, 1), cA + hstep, voffA);
;         if (wr == 1) PG8_BAR;
;         PG8_WAIT_V(4); PG8_BAR;
.Lg4gs_go:
	v_lshlrev_b32_e32 v0, 4, v12
	v_add_u32_e32 v1, 0x2000, v0
	v_ashrrev_i32_e32 v2, 31, v1
	v_lshrrev_b32_e32 v2, 22, v2
	v_add_u32_e32 v2, v1, v2
	v_ashrrev_i32_e32 v8, 10, v2
	v_mul_i32_i24_e32 v2, 0x400, v8
	v_sub_u32_e32 v1, v1, v2
	v_lshrrev_b32_e32 v2, 4, v1
	v_bitop3_b32 v1, v2, v1, 32 bitop3:0x6c
	v_ashrrev_i32_e32 v2, 31, v1
	v_lshrrev_b32_e32 v2, 26, v2
	v_add_u32_e32 v2, v1, v2
	v_ashrrev_i32_e32 v9, 6, v2
	v_and_b32_e32 v2, 0xc0, v2
	v_sub_u32_e32 v1, v1, v2
	v_ashrrev_i16_sdwa v1, v203, sext(v1) dst_sel:DWORD dst_unused:UNUSED_PAD src0_sel:DWORD src1_sel:BYTE_0
	v_bfe_i32 v11, v1, 0, 16
	v_bfe_i32 v1, v12, 27, 1
	v_lshrrev_b32_e32 v1, 22, v1
	v_add_u32_e32 v1, v0, v1
	v_and_b32_e32 v1, 0xfffffc00, v1
	v_sub_u32_e32 v0, v0, v1
	v_lshrrev_b32_e32 v1, 4, v0
	v_ashrrev_i32_e32 v2, 31, v12
	v_bitop3_b32 v0, v1, v0, 32 bitop3:0x6c
	v_lshrrev_b32_e32 v2, 26, v2
	v_lshlrev_b32_e32 v3, 3, v8
	v_ashrrev_i32_e32 v1, 31, v0
	v_add_u32_e32 v2, v12, v2
	v_and_b32_e32 v3, 0xfffff0, v3
	v_lshrrev_b32_e32 v1, 26, v1
	v_ashrrev_i32_e32 v14, 6, v2
	v_add_u32_e32 v3, v9, v3
	s_movk_i32 s0, 0xb00
	v_lshlrev_b32_e32 v4, 5, v8
	v_add_u32_e32 v1, v0, v1
	v_lshlrev_b32_e32 v2, 3, v14
	v_mul_lo_u32 v3, v3, s0
	v_and_b32_e32 v10, 32, v4
	v_ashrrev_i32_e32 v13, 6, v1
	v_and_b32_e32 v2, 0xfffff0, v2
	s_ashr_i32 s15, s12, 6
	v_or_b32_e32 v3, v3, v10
	v_add_u32_e32 v2, v13, v2
	v_and_b32_e32 v1, 0xc0, v1
	v_readlane_b32 s1, v254, 4
	s_ashr_i32 s13, s12, 8
	s_lshl_b32 s25, s15, 10
	v_add_lshl_u32 v146, v3, v11, 1
	v_mul_lo_u32 v2, v2, s0
	v_lshlrev_b32_e32 v3, 5, v14
	v_sub_u32_e32 v0, v0, v1
	s_mul_i32 s0, s1, 0x160000
	v_and_b32_e32 v15, 32, v3
	v_ashrrev_i16_sdwa v0, v203, sext(v0) dst_sel:DWORD dst_unused:UNUSED_PAD src0_sel:DWORD src1_sel:BYTE_0
	s_add_u32 s56, s28, s0
	s_mul_hi_i32 s0, s1, 0x160000
	v_or_b32_e32 v2, v2, v15
	v_bfe_i32 v16, v0, 0, 16
	s_addc_u32 s57, s29, s0
	s_add_i32 s38, s25, 0
	v_add_lshl_u32 v128, v2, v16, 1
	s_add_i32 m0, s38, 0x10000
	v_writelane_b32 v255, s40, 34
	global_load_lds_dwordx4 v128, s[56:57]
	s_add_i32 m0, s38, 0x12000
	s_add_u32 s0, s56, 0xb0000
	global_load_lds_dwordx4 v146, s[56:57]
	s_addc_u32 s1, s57, 0
	s_add_i32 m0, s38, 0x14000
	v_writelane_b32 v255, s41, 35
	global_load_lds_dwordx4 v128, s[0:1]
	s_add_i32 m0, s38, 0x16000
	v_writelane_b32 v255, s42, 36
	global_load_lds_dwordx4 v146, s[0:1]
	v_readlane_b32 s0, v254, 31
	s_mov_b32 s18, s0
	s_mul_i32 s0, s0, 0x160000
	s_add_u32 s50, s8, s0
	s_mul_hi_i32 s0, s18, 0x160000
	s_addc_u32 s51, s9, s0
	s_add_i32 s18, s38, 0x2000
	v_readlane_b32 s1, v254, 32
	s_mov_b32 m0, s38
	s_add_u32 s0, s50, 0xb0000
	global_load_lds_dwordx4 v128, s[50:51]
	s_mov_b32 m0, s18
	s_addc_u32 s1, s51, 0
	s_add_i32 s19, s38, 0x4000
	global_load_lds_dwordx4 v146, s[50:51]
	s_mov_b32 m0, s19
	s_add_i32 s39, s38, 0x6000
	global_load_lds_dwordx4 v128, s[0:1]
	s_mov_b32 m0, s39
	v_writelane_b32 v255, s43, 37
	global_load_lds_dwordx4 v146, s[0:1]
	v_writelane_b32 v255, s36, 32
	v_mov_b32_e32 v147, v129
	s_cmp_eq_u32 s13, 1
	v_writelane_b32 v255, s37, 33
	v_writelane_b32 v255, s34, 30
	v_lshl_add_u64 v[6:7], s[56:57], 0, v[128:129]
	v_lshl_add_u64 v[4:5], s[56:57], 0, v[146:147]
	v_writelane_b32 v255, s35, 31
	v_lshl_add_u64 v[0:1], s[50:51], 0, v[128:129]
	s_cselect_b64 s[0:1], -1, 0
	s_cmp_lg_u32 s13, 1
	v_lshl_add_u64 v[2:3], s[50:51], 0, v[146:147]
	s_cbranch_scc1 .LBB0_1083
	s_barrier
